# L1 out-proj residual epilogue rewritten: 4 batches of 4 row groups, batched residual loads + counted waits
# speedup vs baseline: 1.0192x; 1.0114x over previous
; #define EPI_LOOP_ROWS _Pragma("unroll") for (int ai = 0; ai < 2; ++ai) _Pragma("unroll") for (int m = 0; m < 4; ++m)
; #define EPI_LOOP_BJ _Pragma("unroll") for (int bj = 0; bj < 2; ++bj)
;     DI void operator()(const AccT& acc, int brow, int bcol, int wr, int wc, int fr, int fq) const {
;         EPI_LOOP_BJ { const int col = bcol + bj * 128 + wc * 32 + fq * 8;
;             const f32x4 g0 = *(const f32x4*)(gate + col), g1 = *(const f32x4*)(gate + col + 4); f32x4 b0 = (f32x4){0.f, 0.f, 0.f, 0.f}, b1 = b0; if (bias) { b0 = *(const f32x4*)(bias + col); b1 = *(const f32x4*)(bias + col + 4); }
;             EPI_LOOP_ROWS { const size_t eo = (size_t)(ai * 128 + wr * 64 + m * 16 + fr) * D + col; float* q = base + eo;
;                 f32x4 x0 = (f32x4){0.f, 0.f, 0.f, 0.f}, x1 = x0; if (rmw) { x0 = *(const f32x4*)(src + eo); x1 = *(const f32x4*)(src + eo + 4); }
;                 x0 += g0 * (acc[ai][bj][m][0] + b0); x1 += g1 * (acc[ai][bj][m][1] + b1); *(f32x4*)q = x0; *(f32x4*)(q + 4) = x1; } }
.LBB0_1470:
	v_lshrrev_b32_e32 v128, 1, v136
	v_and_b32_e32 v129, 0x60, v128
	v_and_b32_e32 v128, 24, v128
	v_add3_u32 v158, v129, s2, v128
	v_ashrrev_i32_e32 v159, 31, v158
	v_lshlrev_b64 v[138:139], 2, v[158:159]
	v_lshl_add_u64 v[160:161], s[46:47], 0, v[138:139]
	global_load_dwordx4 v[128:131], v[160:161], off offset:16
	global_load_dwordx4 v[132:135], v[160:161], off
	v_and_b32_e32 v137, 15, v136
	v_ashrrev_i32_e32 v136, 2, v136
	s_movk_i32 s2, 0xffc0
	v_and_or_b32 v164, v136, s2, v137
	v_ashrrev_i32_e32 v165, 31, v164
	v_lshlrev_b64 v[136:137], 12, v[164:165]
	v_lshl_add_u64 v[162:163], s[48:49], 0, v[136:137]
	v_cndmask_b32_e64 v137, 0, 1, s[14:15]
	v_lshl_add_u64 v[166:167], v[162:163], 0, v[138:139]
	v_mov_b32_e32 v136, 0
	v_cmp_ne_u32_e64 s[2:3], 1, v137
	global_load_dwordx4 v[172:175], v[160:161], off offset:528
	global_load_dwordx4 v[136:139], v[160:161], off offset:512
	v_mov_b32_e32 v208, v166
	v_mov_b32_e32 v209, v167
	v_add_co_u32_e32 v210, vcc, 0x10000, v166
	s_nop 1
	v_addc_co_u32_e32 v211, vcc, 0, v167, vcc
	v_add_co_u32_e32 v212, vcc, 0x20000, v166
	s_nop 1
	v_addc_co_u32_e32 v213, vcc, 0, v167, vcc
	v_add_co_u32_e32 v214, vcc, 0x30000, v166
	s_nop 1
	v_addc_co_u32_e32 v215, vcc, 0, v167, vcc
	s_and_b64 vcc, exec, s[14:15]
	s_cbranch_vccz .Lrep_1_0_nold
	global_load_dwordx4 v[176:179], v[208:209], off
	global_load_dwordx4 v[180:183], v[208:209], off offset:16
	global_load_dwordx4 v[184:187], v[210:211], off
	global_load_dwordx4 v[188:191], v[210:211], off offset:16
	global_load_dwordx4 v[192:195], v[212:213], off
	global_load_dwordx4 v[196:199], v[212:213], off offset:16
	global_load_dwordx4 v[200:203], v[214:215], off
	global_load_dwordx4 v[204:207], v[214:215], off offset:16
	s_branch .Lrep_1_0_go
.Lrep_1_0_nold:
	s_waitcnt vmcnt(0)
	v_mov_b32_e32 v176, 0
	v_mov_b32_e32 v177, 0
	v_mov_b32_e32 v178, 0
	v_mov_b32_e32 v179, 0
	v_mov_b32_e32 v180, 0
	v_mov_b32_e32 v181, 0
	v_mov_b32_e32 v182, 0
	v_mov_b32_e32 v183, 0
	v_mov_b32_e32 v184, 0
	v_mov_b32_e32 v185, 0
	v_mov_b32_e32 v186, 0
	v_mov_b32_e32 v187, 0
	v_mov_b32_e32 v188, 0
	v_mov_b32_e32 v189, 0
	v_mov_b32_e32 v190, 0
	v_mov_b32_e32 v191, 0
	v_mov_b32_e32 v192, 0
	v_mov_b32_e32 v193, 0
	v_mov_b32_e32 v194, 0
	v_mov_b32_e32 v195, 0
	v_mov_b32_e32 v196, 0
	v_mov_b32_e32 v197, 0
	v_mov_b32_e32 v198, 0
	v_mov_b32_e32 v199, 0
	v_mov_b32_e32 v200, 0
	v_mov_b32_e32 v201, 0
	v_mov_b32_e32 v202, 0
	v_mov_b32_e32 v203, 0
	v_mov_b32_e32 v204, 0
	v_mov_b32_e32 v205, 0
	v_mov_b32_e32 v206, 0
	v_mov_b32_e32 v207, 0
.Lrep_1_0_go:
	v_pk_add_f32 v[126:127], v[126:127], 0 op_sel_hi:[1,0]
	v_pk_add_f32 v[124:125], v[124:125], 0 op_sel_hi:[1,0]
	v_pk_add_f32 v[120:121], v[120:121], 0 op_sel_hi:[1,0]
	v_pk_add_f32 v[122:123], v[122:123], 0 op_sel_hi:[1,0]
	s_waitcnt vmcnt(6)
	v_pk_fma_f32 v[126:127], v[126:127], v[134:135], v[178:179]
	v_pk_fma_f32 v[124:125], v[124:125], v[132:133], v[176:177]
	v_pk_fma_f32 v[120:121], v[120:121], v[128:129], v[180:181]
	v_pk_fma_f32 v[122:123], v[122:123], v[130:131], v[182:183]
	global_store_dwordx4 v[208:209], v[124:127], off
	global_store_dwordx4 v[208:209], v[120:123], off offset:16
	v_pk_add_f32 v[118:119], v[118:119], 0 op_sel_hi:[1,0]
	v_pk_add_f32 v[116:117], v[116:117], 0 op_sel_hi:[1,0]
	v_pk_add_f32 v[112:113], v[112:113], 0 op_sel_hi:[1,0]
	v_pk_add_f32 v[114:115], v[114:115], 0 op_sel_hi:[1,0]
	s_waitcnt vmcnt(6)
	v_pk_fma_f32 v[118:119], v[118:119], v[134:135], v[186:187]
	v_pk_fma_f32 v[116:117], v[116:117], v[132:133], v[184:185]
	v_pk_fma_f32 v[112:113], v[112:113], v[128:129], v[188:189]
	v_pk_fma_f32 v[114:115], v[114:115], v[130:131], v[190:191]
	global_store_dwordx4 v[210:211], v[116:119], off
	global_store_dwordx4 v[210:211], v[112:115], off offset:16
	v_pk_add_f32 v[110:111], v[110:111], 0 op_sel_hi:[1,0]
	v_pk_add_f32 v[108:109], v[108:109], 0 op_sel_hi:[1,0]
	v_pk_add_f32 v[104:105], v[104:105], 0 op_sel_hi:[1,0]
	v_pk_add_f32 v[106:107], v[106:107], 0 op_sel_hi:[1,0]
	s_waitcnt vmcnt(6)
	v_pk_fma_f32 v[110:111], v[110:111], v[134:135], v[194:195]
	v_pk_fma_f32 v[108:109], v[108:109], v[132:133], v[192:193]
	v_pk_fma_f32 v[104:105], v[104:105], v[128:129], v[196:197]
	v_pk_fma_f32 v[106:107], v[106:107], v[130:131], v[198:199]
	global_store_dwordx4 v[212:213], v[108:111], off
	global_store_dwordx4 v[212:213], v[104:107], off offset:16
	v_pk_add_f32 v[102:103], v[102:103], 0 op_sel_hi:[1,0]
	v_pk_add_f32 v[100:101], v[100:101], 0 op_sel_hi:[1,0]
	v_pk_add_f32 v[96:97], v[96:97], 0 op_sel_hi:[1,0]
	v_pk_add_f32 v[98:99], v[98:99], 0 op_sel_hi:[1,0]
	s_waitcnt vmcnt(6)
	v_pk_fma_f32 v[102:103], v[102:103], v[134:135], v[202:203]
	v_pk_fma_f32 v[100:101], v[100:101], v[132:133], v[200:201]
	v_pk_fma_f32 v[96:97], v[96:97], v[128:129], v[204:205]
	v_pk_fma_f32 v[98:99], v[98:99], v[130:131], v[206:207]
	global_store_dwordx4 v[214:215], v[100:103], off
	global_store_dwordx4 v[214:215], v[96:99], off offset:16
	v_add_co_u32_e32 v208, vcc, 0x80000, v166
	s_nop 1
	v_addc_co_u32_e32 v209, vcc, 0, v167, vcc
	v_add_co_u32_e32 v210, vcc, 0x90000, v166
	s_nop 1
	v_addc_co_u32_e32 v211, vcc, 0, v167, vcc
	v_add_co_u32_e32 v212, vcc, 0xa0000, v166
	s_nop 1
	v_addc_co_u32_e32 v213, vcc, 0, v167, vcc
	v_add_co_u32_e32 v214, vcc, 0xb0000, v166
	s_nop 1
	v_addc_co_u32_e32 v215, vcc, 0, v167, vcc
	s_and_b64 vcc, exec, s[14:15]
	s_cbranch_vccz .Lrep_1_1_nold
	global_load_dwordx4 v[176:179], v[208:209], off
	global_load_dwordx4 v[180:183], v[208:209], off offset:16
	global_load_dwordx4 v[184:187], v[210:211], off
	global_load_dwordx4 v[188:191], v[210:211], off offset:16
	global_load_dwordx4 v[192:195], v[212:213], off
	global_load_dwordx4 v[196:199], v[212:213], off offset:16
	global_load_dwordx4 v[200:203], v[214:215], off
	global_load_dwordx4 v[204:207], v[214:215], off offset:16
	s_branch .Lrep_1_1_go
; #define EPI_LOOP_ROWS _Pragma("unroll") for (int ai = 0; ai < 2; ++ai) _Pragma("unroll") for (int m = 0; m < 4; ++m)
; #define EPI_LOOP_BJ _Pragma("unroll") for (int bj = 0; bj < 2; ++bj)
;     DI void operator()(const AccT& acc, int brow, int bcol, int wr, int wc, int fr, int fq) const {
;         EPI_LOOP_BJ { const int col = bcol + bj * 128 + wc * 32 + fq * 8;
;             const f32x4 g0 = *(const f32x4*)(gate + col), g1 = *(const f32x4*)(gate + col + 4); f32x4 b0 = (f32x4){0.f, 0.f, 0.f, 0.f}, b1 = b0; if (bias) { b0 = *(const f32x4*)(bias + col); b1 = *(const f32x4*)(bias + col + 4); }
;             EPI_LOOP_ROWS { const size_t eo = (size_t)(ai * 128 + wr * 64 + m * 16 + fr) * D + col; float* q = base + eo;
;                 f32x4 x0 = (f32x4){0.f, 0.f, 0.f, 0.f}, x1 = x0; if (rmw) { x0 = *(const f32x4*)(src + eo); x1 = *(const f32x4*)(src + eo + 4); }
;                 x0 += g0 * (acc[ai][bj][m][0] + b0); x1 += g1 * (acc[ai][bj][m][1] + b1); *(f32x4*)q = x0; *(f32x4*)(q + 4) = x1; } }
.Lrep_1_1_nold:
	v_mov_b32_e32 v176, 0
	v_mov_b32_e32 v177, 0
	v_mov_b32_e32 v178, 0
	v_mov_b32_e32 v179, 0
	v_mov_b32_e32 v180, 0
	v_mov_b32_e32 v181, 0
	v_mov_b32_e32 v182, 0
	v_mov_b32_e32 v183, 0
	v_mov_b32_e32 v184, 0
	v_mov_b32_e32 v185, 0
	v_mov_b32_e32 v186, 0
	v_mov_b32_e32 v187, 0
	v_mov_b32_e32 v188, 0
	v_mov_b32_e32 v189, 0
	v_mov_b32_e32 v190, 0
	v_mov_b32_e32 v191, 0
	v_mov_b32_e32 v192, 0
	v_mov_b32_e32 v193, 0
	v_mov_b32_e32 v194, 0
	v_mov_b32_e32 v195, 0
	v_mov_b32_e32 v196, 0
	v_mov_b32_e32 v197, 0
	v_mov_b32_e32 v198, 0
	v_mov_b32_e32 v199, 0
	v_mov_b32_e32 v200, 0
	v_mov_b32_e32 v201, 0
	v_mov_b32_e32 v202, 0
	v_mov_b32_e32 v203, 0
	v_mov_b32_e32 v204, 0
	v_mov_b32_e32 v205, 0
	v_mov_b32_e32 v206, 0
	v_mov_b32_e32 v207, 0
.Lrep_1_1_go:
	v_pk_add_f32 v[94:95], v[94:95], 0 op_sel_hi:[1,0]
	v_pk_add_f32 v[92:93], v[92:93], 0 op_sel_hi:[1,0]
	v_pk_add_f32 v[90:91], v[90:91], 0 op_sel_hi:[1,0]
	v_pk_add_f32 v[88:89], v[88:89], 0 op_sel_hi:[1,0]
	s_waitcnt vmcnt(6)
	v_pk_fma_f32 v[94:95], v[94:95], v[134:135], v[178:179]
	v_pk_fma_f32 v[92:93], v[92:93], v[132:133], v[176:177]
	v_pk_fma_f32 v[90:91], v[90:91], v[130:131], v[182:183]
	v_pk_fma_f32 v[88:89], v[88:89], v[128:129], v[180:181]
	global_store_dwordx4 v[208:209], v[92:95], off
	global_store_dwordx4 v[208:209], v[88:91], off offset:16
	v_pk_add_f32 v[86:87], v[86:87], 0 op_sel_hi:[1,0]
	v_pk_add_f32 v[84:85], v[84:85], 0 op_sel_hi:[1,0]
	v_pk_add_f32 v[80:81], v[80:81], 0 op_sel_hi:[1,0]
	v_pk_add_f32 v[82:83], v[82:83], 0 op_sel_hi:[1,0]
	s_waitcnt vmcnt(6)
	v_pk_fma_f32 v[86:87], v[86:87], v[134:135], v[186:187]
	v_pk_fma_f32 v[84:85], v[84:85], v[132:133], v[184:185]
	v_pk_fma_f32 v[80:81], v[80:81], v[128:129], v[188:189]
	v_pk_fma_f32 v[82:83], v[82:83], v[130:131], v[190:191]
	global_store_dwordx4 v[210:211], v[84:87], off
	global_store_dwordx4 v[210:211], v[80:83], off offset:16
	v_pk_add_f32 v[74:75], v[74:75], 0 op_sel_hi:[1,0]
	v_pk_add_f32 v[78:79], v[78:79], 0 op_sel_hi:[1,0]
	v_pk_add_f32 v[76:77], v[76:77], 0 op_sel_hi:[1,0]
	v_pk_add_f32 v[72:73], v[72:73], 0 op_sel_hi:[1,0]
	s_waitcnt vmcnt(6)
	v_pk_fma_f32 v[74:75], v[74:75], v[130:131], v[198:199]
	v_pk_fma_f32 v[78:79], v[78:79], v[134:135], v[194:195]
	v_pk_fma_f32 v[76:77], v[76:77], v[132:133], v[192:193]
	v_pk_fma_f32 v[72:73], v[72:73], v[128:129], v[196:197]
	global_store_dwordx4 v[212:213], v[76:79], off
	global_store_dwordx4 v[212:213], v[72:75], off offset:16
	v_pk_add_f32 v[70:71], v[70:71], 0 op_sel_hi:[1,0]
	v_pk_add_f32 v[68:69], v[68:69], 0 op_sel_hi:[1,0]
	v_pk_add_f32 v[66:67], v[66:67], 0 op_sel_hi:[1,0]
	v_pk_add_f32 v[64:65], v[64:65], 0 op_sel_hi:[1,0]
	s_waitcnt vmcnt(6)
	v_pk_fma_f32 v[70:71], v[70:71], v[134:135], v[202:203]
	v_pk_fma_f32 v[68:69], v[68:69], v[132:133], v[200:201]
	v_pk_fma_f32 v[66:67], v[66:67], v[130:131], v[206:207]
	v_pk_fma_f32 v[64:65], v[64:65], v[128:129], v[204:205]
	global_store_dwordx4 v[214:215], v[68:71], off
	global_store_dwordx4 v[214:215], v[64:67], off offset:16
	v_add_co_u32_e32 v208, vcc, 0x200, v166
	s_nop 1
	v_addc_co_u32_e32 v209, vcc, 0, v167, vcc
	v_add_co_u32_e32 v210, vcc, 0x10200, v166
	s_nop 1
	v_addc_co_u32_e32 v211, vcc, 0, v167, vcc
	v_add_co_u32_e32 v212, vcc, 0x20200, v166
	s_nop 1
	v_addc_co_u32_e32 v213, vcc, 0, v167, vcc
	v_add_co_u32_e32 v214, vcc, 0x30200, v166
	s_nop 1
	v_addc_co_u32_e32 v215, vcc, 0, v167, vcc
	s_and_b64 vcc, exec, s[14:15]
	s_cbranch_vccz .Lrep_1_2_nold
	global_load_dwordx4 v[176:179], v[208:209], off
	global_load_dwordx4 v[180:183], v[208:209], off offset:16
	global_load_dwordx4 v[184:187], v[210:211], off
	global_load_dwordx4 v[188:191], v[210:211], off offset:16
	global_load_dwordx4 v[192:195], v[212:213], off
	global_load_dwordx4 v[196:199], v[212:213], off offset:16
	global_load_dwordx4 v[200:203], v[214:215], off
	global_load_dwordx4 v[204:207], v[214:215], off offset:16
	s_branch .Lrep_1_2_go

; #define EPI_LOOP_ROWS _Pragma("unroll") for (int ai = 0; ai < 2; ++ai) _Pragma("unroll") for (int m = 0; m < 4; ++m)
; #define EPI_LOOP_BJ _Pragma("unroll") for (int bj = 0; bj < 2; ++bj)
;     DI void operator()(const AccT& acc, int brow, int bcol, int wr, int wc, int fr, int fq) const {
;         EPI_LOOP_BJ { const int col = bcol + bj * 128 + wc * 32 + fq * 8;
;             const f32x4 g0 = *(const f32x4*)(gate + col), g1 = *(const f32x4*)(gate + col + 4); f32x4 b0 = (f32x4){0.f, 0.f, 0.f, 0.f}, b1 = b0; if (bias) { b0 = *(const f32x4*)(bias + col); b1 = *(const f32x4*)(bias + col + 4); }
;             EPI_LOOP_ROWS { const size_t eo = (size_t)(ai * 128 + wr * 64 + m * 16 + fr) * D + col; float* q = base + eo;
;                 f32x4 x0 = (f32x4){0.f, 0.f, 0.f, 0.f}, x1 = x0; if (rmw) { x0 = *(const f32x4*)(src + eo); x1 = *(const f32x4*)(src + eo + 4); }
;                 x0 += g0 * (acc[ai][bj][m][0] + b0); x1 += g1 * (acc[ai][bj][m][1] + b1); *(f32x4*)q = x0; *(f32x4*)(q + 4) = x1; } }
.Lrep_1_2_go:
	v_pk_add_f32 v[62:63], v[62:63], 0 op_sel_hi:[1,0]
	v_pk_add_f32 v[60:61], v[60:61], 0 op_sel_hi:[1,0]
	v_pk_add_f32 v[58:59], v[58:59], 0 op_sel_hi:[1,0]
	v_pk_add_f32 v[56:57], v[56:57], 0 op_sel_hi:[1,0]
	s_waitcnt vmcnt(6)
	v_pk_fma_f32 v[62:63], v[62:63], v[138:139], v[178:179]
	v_pk_fma_f32 v[60:61], v[60:61], v[136:137], v[176:177]
	v_pk_fma_f32 v[58:59], v[58:59], v[174:175], v[182:183]
	v_pk_fma_f32 v[56:57], v[56:57], v[172:173], v[180:181]
	global_store_dwordx4 v[208:209], v[60:63], off
	global_store_dwordx4 v[208:209], v[56:59], off offset:16
	v_pk_add_f32 v[54:55], v[54:55], 0 op_sel_hi:[1,0]
	v_pk_add_f32 v[52:53], v[52:53], 0 op_sel_hi:[1,0]
	v_pk_add_f32 v[50:51], v[50:51], 0 op_sel_hi:[1,0]
	v_pk_add_f32 v[48:49], v[48:49], 0 op_sel_hi:[1,0]
	s_waitcnt vmcnt(6)
	v_pk_fma_f32 v[54:55], v[54:55], v[138:139], v[186:187]
	v_pk_fma_f32 v[52:53], v[52:53], v[136:137], v[184:185]
	v_pk_fma_f32 v[50:51], v[50:51], v[174:175], v[190:191]
	v_pk_fma_f32 v[48:49], v[48:49], v[172:173], v[188:189]
	global_store_dwordx4 v[210:211], v[52:55], off
	global_store_dwordx4 v[210:211], v[48:51], off offset:16
	v_pk_add_f32 v[46:47], v[46:47], 0 op_sel_hi:[1,0]
	v_pk_add_f32 v[44:45], v[44:45], 0 op_sel_hi:[1,0]
	v_pk_add_f32 v[42:43], v[42:43], 0 op_sel_hi:[1,0]
	v_pk_add_f32 v[40:41], v[40:41], 0 op_sel_hi:[1,0]
	s_waitcnt vmcnt(6)
	v_pk_fma_f32 v[46:47], v[46:47], v[138:139], v[194:195]
	v_pk_fma_f32 v[44:45], v[44:45], v[136:137], v[192:193]
	v_pk_fma_f32 v[42:43], v[42:43], v[174:175], v[198:199]
	v_pk_fma_f32 v[40:41], v[40:41], v[172:173], v[196:197]
	global_store_dwordx4 v[212:213], v[44:47], off
	global_store_dwordx4 v[212:213], v[40:43], off offset:16
	v_pk_add_f32 v[38:39], v[38:39], 0 op_sel_hi:[1,0]
	v_pk_add_f32 v[36:37], v[36:37], 0 op_sel_hi:[1,0]
	v_pk_add_f32 v[34:35], v[34:35], 0 op_sel_hi:[1,0]
	v_pk_add_f32 v[32:33], v[32:33], 0 op_sel_hi:[1,0]
	s_waitcnt vmcnt(6)
	v_pk_fma_f32 v[38:39], v[38:39], v[138:139], v[202:203]
	v_pk_fma_f32 v[36:37], v[36:37], v[136:137], v[200:201]
	v_pk_fma_f32 v[34:35], v[34:35], v[174:175], v[206:207]
	v_pk_fma_f32 v[32:33], v[32:33], v[172:173], v[204:205]
	global_store_dwordx4 v[214:215], v[36:39], off
	global_store_dwordx4 v[214:215], v[32:35], off offset:16
	v_add_co_u32_e32 v208, vcc, 0x80200, v166
	s_nop 1
	v_addc_co_u32_e32 v209, vcc, 0, v167, vcc
	v_add_co_u32_e32 v210, vcc, 0x90200, v166
	s_nop 1
	v_addc_co_u32_e32 v211, vcc, 0, v167, vcc
	v_add_co_u32_e32 v212, vcc, 0xa0200, v166
	s_nop 1
	v_addc_co_u32_e32 v213, vcc, 0, v167, vcc
	v_add_co_u32_e32 v214, vcc, 0xb0200, v166
	s_nop 1
	v_addc_co_u32_e32 v215, vcc, 0, v167, vcc
	s_and_b64 vcc, exec, s[14:15]
	s_cbranch_vccz .Lrep_1_3_nold
	global_load_dwordx4 v[176:179], v[208:209], off
	global_load_dwordx4 v[180:183], v[208:209], off offset:16
	global_load_dwordx4 v[184:187], v[210:211], off
	global_load_dwordx4 v[188:191], v[210:211], off offset:16
	global_load_dwordx4 v[192:195], v[212:213], off
	global_load_dwordx4 v[196:199], v[212:213], off offset:16
	global_load_dwordx4 v[200:203], v[214:215], off
	global_load_dwordx4 v[204:207], v[214:215], off offset:16
	s_branch .Lrep_1_3_go

; #define BAR __builtin_amdgcn_s_barrier()
; #define EPI_LOOP_ROWS _Pragma("unroll") for (int ai = 0; ai < 2; ++ai) _Pragma("unroll") for (int m = 0; m < 4; ++m)
; #define EPI_LOOP_BJ _Pragma("unroll") for (int bj = 0; bj < 2; ++bj)
; template <class Get, class Epi>
; DI void gemm_loop(int ntiles, int ld, char* shm, const Get& get, const Epi& epi) {
;     ...
;         if (!has_next) break;
;         G_ZERO;
;         cur = nxt; cA = nA; cB = nB; L = Ln;
;         if (wr == 1) BAR;
;     DI void operator()(const AccT& acc, int brow, int bcol, int wr, int wc, int fr, int fq) const {
;         EPI_LOOP_BJ { const int col = bcol + bj * 128 + wc * 32 + fq * 8;
;             const f32x4 g0 = *(const f32x4*)(gate + col), g1 = *(const f32x4*)(gate + col + 4); f32x4 b0 = (f32x4){0.f, 0.f, 0.f, 0.f}, b1 = b0; if (bias) { b0 = *(const f32x4*)(bias + col); b1 = *(const f32x4*)(bias + col + 4); }
;             EPI_LOOP_ROWS { const size_t eo = (size_t)(ai * 128 + wr * 64 + m * 16 + fr) * D + col; float* q = base + eo;
;                 f32x4 x0 = (f32x4){0.f, 0.f, 0.f, 0.f}, x1 = x0; if (rmw) { x0 = *(const f32x4*)(src + eo); x1 = *(const f32x4*)(src + eo + 4); }
;                 x0 += g0 * (acc[ai][bj][m][0] + b0); x1 += g1 * (acc[ai][bj][m][1] + b1); *(f32x4*)q = x0; *(f32x4*)(q + 4) = x1; } }
.Lrep_1_3_go:
	v_pk_add_f32 v[30:31], v[30:31], 0 op_sel_hi:[1,0]
	v_pk_add_f32 v[28:29], v[28:29], 0 op_sel_hi:[1,0]
	v_pk_add_f32 v[26:27], v[26:27], 0 op_sel_hi:[1,0]
	v_pk_add_f32 v[24:25], v[24:25], 0 op_sel_hi:[1,0]
	s_waitcnt vmcnt(6)
	v_pk_fma_f32 v[30:31], v[30:31], v[138:139], v[178:179]
	v_pk_fma_f32 v[28:29], v[28:29], v[136:137], v[176:177]
	v_pk_fma_f32 v[26:27], v[26:27], v[174:175], v[182:183]
	v_pk_fma_f32 v[24:25], v[24:25], v[172:173], v[180:181]
	global_store_dwordx4 v[208:209], v[28:31], off
	global_store_dwordx4 v[208:209], v[24:27], off offset:16
	v_pk_add_f32 v[22:23], v[22:23], 0 op_sel_hi:[1,0]
	v_pk_add_f32 v[20:21], v[20:21], 0 op_sel_hi:[1,0]
	v_pk_add_f32 v[18:19], v[18:19], 0 op_sel_hi:[1,0]
	v_pk_add_f32 v[16:17], v[16:17], 0 op_sel_hi:[1,0]
	s_waitcnt vmcnt(6)
	v_pk_fma_f32 v[22:23], v[22:23], v[138:139], v[186:187]
	v_pk_fma_f32 v[20:21], v[20:21], v[136:137], v[184:185]
	v_pk_fma_f32 v[18:19], v[18:19], v[174:175], v[190:191]
	v_pk_fma_f32 v[16:17], v[16:17], v[172:173], v[188:189]
	global_store_dwordx4 v[210:211], v[20:23], off
	global_store_dwordx4 v[210:211], v[16:19], off offset:16
	v_pk_add_f32 v[14:15], v[14:15], 0 op_sel_hi:[1,0]
	v_pk_add_f32 v[12:13], v[12:13], 0 op_sel_hi:[1,0]
	v_pk_add_f32 v[8:9], v[8:9], 0 op_sel_hi:[1,0]
	v_pk_add_f32 v[10:11], v[10:11], 0 op_sel_hi:[1,0]
	s_waitcnt vmcnt(6)
	v_pk_fma_f32 v[14:15], v[14:15], v[138:139], v[194:195]
	v_pk_fma_f32 v[12:13], v[12:13], v[136:137], v[192:193]
	v_pk_fma_f32 v[8:9], v[8:9], v[172:173], v[196:197]
	v_pk_fma_f32 v[10:11], v[10:11], v[174:175], v[198:199]
	global_store_dwordx4 v[212:213], v[12:15], off
	global_store_dwordx4 v[212:213], v[8:11], off offset:16
	v_pk_add_f32 v[6:7], v[6:7], 0 op_sel_hi:[1,0]
	v_pk_add_f32 v[4:5], v[4:5], 0 op_sel_hi:[1,0]
	v_pk_add_f32 v[2:3], v[2:3], 0 op_sel_hi:[1,0]
	v_pk_add_f32 v[0:1], v[0:1], 0 op_sel_hi:[1,0]
	s_waitcnt vmcnt(6)
	v_pk_fma_f32 v[6:7], v[6:7], v[138:139], v[202:203]
	v_pk_fma_f32 v[4:5], v[4:5], v[136:137], v[200:201]
	v_pk_fma_f32 v[2:3], v[2:3], v[174:175], v[206:207]
	v_pk_fma_f32 v[0:1], v[0:1], v[172:173], v[204:205]
	global_store_dwordx4 v[214:215], v[4:7], off
	global_store_dwordx4 v[214:215], v[0:3], off offset:16
	s_andn2_b64 vcc, exec, s[34:35]
	s_mov_b64 s[2:3], -1
	s_cbranch_vccnz .LBB0_1452
	s_andn2_b64 vcc, exec, s[8:9]
	s_cbranch_vccnz .LBB0_1451
	s_barrier
	s_branch .LBB0_1451
